# tile-loop rewrite plus 688 unreachable s_nop so the code after it keeps its old placement (placement sensitivity found)
# speedup vs baseline: 1.0060x; 1.0060x over previous
.Lp0_rot:
	s_cmpk_ge_u32 s13, 0xc40
	s_cbranch_scc1 .Lp0_done
	s_mov_b64 s[36:37], s[44:45]
	s_mov_b64 s[38:39], s[46:47]
	v_mov_b32_e32 v46, v51
	s_mov_b32 s14, s50
	s_add_i32 s12, s12, 1
	s_min_u32 s12, s12, 2
	s_add_i32 s13, s13, s23
	s_branch .Lp0_loop
	s_nop 0
	s_nop 0
	s_nop 0
	s_nop 0
	s_nop 0
	s_nop 0
	s_nop 0
	s_nop 0
	s_nop 0
	s_nop 0
	s_nop 0
	s_nop 0
	s_nop 0
	s_nop 0
	s_nop 0
	s_nop 0
	s_nop 0
	s_nop 0
	s_nop 0
	s_nop 0
	s_nop 0
	s_nop 0
	s_nop 0
	s_nop 0
	s_nop 0
	s_nop 0
	s_nop 0
	s_nop 0
	s_nop 0
	s_nop 0
	s_nop 0
	s_nop 0
	s_nop 0
	s_nop 0
	s_nop 0
	s_nop 0
	s_nop 0
	s_nop 0
	s_nop 0
	s_nop 0
	s_nop 0
	s_nop 0
	s_nop 0
	s_nop 0
	s_nop 0
	s_nop 0
	s_nop 0
	s_nop 0
	s_nop 0
	s_nop 0
	s_nop 0
	s_nop 0
	s_nop 0
	s_nop 0
	s_nop 0
	s_nop 0
	s_nop 0
	s_nop 0
	s_nop 0
	s_nop 0
	s_nop 0
	s_nop 0
	s_nop 0
	s_nop 0
	s_nop 0
	s_nop 0
	s_nop 0
	s_nop 0
	s_nop 0
	s_nop 0
	s_nop 0
	s_nop 0
	s_nop 0
	s_nop 0
	s_nop 0
	s_nop 0
	s_nop 0
	s_nop 0
	s_nop 0
	s_nop 0
	s_nop 0
	s_nop 0
	s_nop 0
	s_nop 0
	s_nop 0
	s_nop 0
	s_nop 0
	s_nop 0
	s_nop 0
	s_nop 0
	s_nop 0
	s_nop 0
	s_nop 0
	s_nop 0
	s_nop 0
	s_nop 0
	s_nop 0
	s_nop 0
	s_nop 0
	s_nop 0
	s_nop 0
	s_nop 0
	s_nop 0
	s_nop 0
	s_nop 0
	s_nop 0
	s_nop 0
	s_nop 0
	s_nop 0
	s_nop 0
	s_nop 0
	s_nop 0
	s_nop 0
	s_nop 0
	s_nop 0
	s_nop 0
	s_nop 0
	s_nop 0
	s_nop 0
	s_nop 0
	s_nop 0
	s_nop 0
	s_nop 0
	s_nop 0
	s_nop 0
	s_nop 0
	s_nop 0
	s_nop 0
	s_nop 0
	s_nop 0
	s_nop 0
	s_nop 0
	s_nop 0
	s_nop 0
	s_nop 0
	s_nop 0
	s_nop 0
	s_nop 0
	s_nop 0
	s_nop 0
	s_nop 0
	s_nop 0
	s_nop 0
	s_nop 0
	s_nop 0
	s_nop 0
	s_nop 0
	s_nop 0
	s_nop 0
	s_nop 0
	s_nop 0
	s_nop 0
	s_nop 0
	s_nop 0
	s_nop 0
	s_nop 0
	s_nop 0
	s_nop 0
	s_nop 0
	s_nop 0
	s_nop 0
	s_nop 0
	s_nop 0
	s_nop 0
	s_nop 0
	s_nop 0
	s_nop 0
	s_nop 0
	s_nop 0
	s_nop 0
	s_nop 0
	s_nop 0
	s_nop 0
	s_nop 0
	s_nop 0
	s_nop 0
	s_nop 0
	s_nop 0
	s_nop 0
	s_nop 0
	s_nop 0
	s_nop 0
	s_nop 0
	s_nop 0
	s_nop 0
	s_nop 0
	s_nop 0
	s_nop 0
	s_nop 0
	s_nop 0
	s_nop 0
	s_nop 0
	s_nop 0
	s_nop 0
	s_nop 0
	s_nop 0
	s_nop 0
	s_nop 0
	s_nop 0
	s_nop 0
	s_nop 0
	s_nop 0
	s_nop 0
	s_nop 0
	s_nop 0
	s_nop 0
	s_nop 0
	s_nop 0
	s_nop 0
	s_nop 0
	s_nop 0
	s_nop 0
	s_nop 0
	s_nop 0
	s_nop 0
	s_nop 0
	s_nop 0
	s_nop 0
	s_nop 0
	s_nop 0
	s_nop 0
	s_nop 0
	s_nop 0
	s_nop 0
	s_nop 0
	s_nop 0
	s_nop 0
	s_nop 0
	s_nop 0
	s_nop 0
	s_nop 0
	s_nop 0
	s_nop 0
	s_nop 0
	s_nop 0
	s_nop 0
	s_nop 0
	s_nop 0
	s_nop 0
	s_nop 0
	s_nop 0
	s_nop 0
	s_nop 0
	s_nop 0
	s_nop 0
	s_nop 0
	s_nop 0
	s_nop 0
	s_nop 0
	s_nop 0
	s_nop 0
	s_nop 0
	s_nop 0
	s_nop 0
	s_nop 0
	s_nop 0
	s_nop 0
	s_nop 0
	s_nop 0
	s_nop 0
	s_nop 0
	s_nop 0
	s_nop 0
	s_nop 0
	s_nop 0
	s_nop 0
	s_nop 0
	s_nop 0
	s_nop 0
	s_nop 0
	s_nop 0
	s_nop 0
	s_nop 0
	s_nop 0
	s_nop 0
	s_nop 0
	s_nop 0
	s_nop 0
	s_nop 0
	s_nop 0
	s_nop 0
	s_nop 0
	s_nop 0
	s_nop 0
	s_nop 0
	s_nop 0
	s_nop 0
	s_nop 0
	s_nop 0
	s_nop 0
	s_nop 0
	s_nop 0
	s_nop 0
	s_nop 0
	s_nop 0
	s_nop 0
	s_nop 0
	s_nop 0
	s_nop 0
	s_nop 0
	s_nop 0
	s_nop 0
	s_nop 0
	s_nop 0
	s_nop 0
	s_nop 0
	s_nop 0
	s_nop 0
	s_nop 0
	s_nop 0
	s_nop 0
	s_nop 0
	s_nop 0
	s_nop 0
	s_nop 0
	s_nop 0
	s_nop 0
	s_nop 0
	s_nop 0
	s_nop 0
	s_nop 0
	s_nop 0
	s_nop 0
	s_nop 0
	s_nop 0
	s_nop 0
	s_nop 0
	s_nop 0
	s_nop 0
	s_nop 0
	s_nop 0
	s_nop 0
	s_nop 0
	s_nop 0
	s_nop 0
	s_nop 0
	s_nop 0
	s_nop 0
	s_nop 0
	s_nop 0
	s_nop 0
	s_nop 0
	s_nop 0
	s_nop 0
	s_nop 0
	s_nop 0
	s_nop 0
	s_nop 0
	s_nop 0
	s_nop 0
	s_nop 0
	s_nop 0
	s_nop 0
	s_nop 0
	s_nop 0
	s_nop 0
	s_nop 0
	s_nop 0
	s_nop 0
	s_nop 0
	s_nop 0
	s_nop 0
	s_nop 0
	s_nop 0
	s_nop 0
	s_nop 0
	s_nop 0
	s_nop 0
	s_nop 0
	s_nop 0
	s_nop 0
	s_nop 0
	s_nop 0
	s_nop 0
	s_nop 0
	s_nop 0
	s_nop 0
	s_nop 0
	s_nop 0
	s_nop 0
	s_nop 0
	s_nop 0
	s_nop 0
	s_nop 0
	s_nop 0
	s_nop 0
	s_nop 0
	s_nop 0
	s_nop 0
	s_nop 0
	s_nop 0
	s_nop 0
	s_nop 0
	s_nop 0
	s_nop 0
	s_nop 0
	s_nop 0
	s_nop 0
	s_nop 0
	s_nop 0
	s_nop 0
	s_nop 0
	s_nop 0
	s_nop 0
	s_nop 0
	s_nop 0
	s_nop 0
	s_nop 0
	s_nop 0
	s_nop 0
	s_nop 0
	s_nop 0
	s_nop 0
	s_nop 0
	s_nop 0
	s_nop 0
	s_nop 0
	s_nop 0
	s_nop 0
	s_nop 0
	s_nop 0
	s_nop 0
	s_nop 0
	s_nop 0
	s_nop 0
	s_nop 0
	s_nop 0
	s_nop 0
	s_nop 0
	s_nop 0
	s_nop 0
	s_nop 0
	s_nop 0
	s_nop 0
	s_nop 0
	s_nop 0
	s_nop 0
	s_nop 0
	s_nop 0
	s_nop 0
	s_nop 0
	s_nop 0
	s_nop 0
	s_nop 0
	s_nop 0
	s_nop 0
	s_nop 0
	s_nop 0
	s_nop 0
	s_nop 0
	s_nop 0
	s_nop 0
	s_nop 0
	s_nop 0
	s_nop 0
	s_nop 0
	s_nop 0
	s_nop 0
	s_nop 0
	s_nop 0
	s_nop 0
	s_nop 0
	s_nop 0
	s_nop 0
	s_nop 0
	s_nop 0
	s_nop 0
	s_nop 0
	s_nop 0
	s_nop 0
	s_nop 0
	s_nop 0
	s_nop 0
	s_nop 0
	s_nop 0
	s_nop 0
	s_nop 0
	s_nop 0
	s_nop 0
	s_nop 0
	s_nop 0
	s_nop 0
	s_nop 0
	s_nop 0
	s_nop 0
	s_nop 0
	s_nop 0
	s_nop 0
	s_nop 0
	s_nop 0
	s_nop 0
	s_nop 0
	s_nop 0
	s_nop 0
	s_nop 0
	s_nop 0
	s_nop 0
	s_nop 0
	s_nop 0
	s_nop 0
	s_nop 0
	s_nop 0
	s_nop 0
	s_nop 0
	s_nop 0
	s_nop 0
	s_nop 0
	s_nop 0
	s_nop 0
	s_nop 0
	s_nop 0
	s_nop 0
	s_nop 0
	s_nop 0
	s_nop 0
	s_nop 0
	s_nop 0
	s_nop 0
	s_nop 0
	s_nop 0
	s_nop 0
	s_nop 0
	s_nop 0
	s_nop 0
	s_nop 0
	s_nop 0
	s_nop 0
	s_nop 0
	s_nop 0
	s_nop 0
	s_nop 0
	s_nop 0
	s_nop 0
	s_nop 0
	s_nop 0
	s_nop 0
	s_nop 0
	s_nop 0
	s_nop 0
	s_nop 0
	s_nop 0
	s_nop 0
	s_nop 0
	s_nop 0
	s_nop 0
	s_nop 0
	s_nop 0
	s_nop 0
	s_nop 0
	s_nop 0
	s_nop 0
	s_nop 0
	s_nop 0
	s_nop 0
	s_nop 0
	s_nop 0
	s_nop 0
	s_nop 0
	s_nop 0
	s_nop 0
	s_nop 0
	s_nop 0
	s_nop 0
	s_nop 0
	s_nop 0
	s_nop 0
	s_nop 0
	s_nop 0
	s_nop 0
	s_nop 0
	s_nop 0
	s_nop 0
	s_nop 0
	s_nop 0
	s_nop 0
	s_nop 0
	s_nop 0
	s_nop 0
	s_nop 0
	s_nop 0
	s_nop 0
	s_nop 0
	s_nop 0
	s_nop 0
	s_nop 0
	s_nop 0
	s_nop 0
	s_nop 0
	s_nop 0
	s_nop 0
	s_nop 0
	s_nop 0
	s_nop 0
	s_nop 0
	s_nop 0
	s_nop 0
	s_nop 0
	s_nop 0
	s_nop 0
	s_nop 0
	s_nop 0
	s_nop 0
	s_nop 0
	s_nop 0
	s_nop 0
	s_nop 0
	s_nop 0
	s_nop 0
	s_nop 0
	s_nop 0
	s_nop 0
	s_nop 0
	s_nop 0
	s_nop 0
	s_nop 0
	s_nop 0
	s_nop 0
	s_nop 0
	s_nop 0
	s_nop 0
	s_nop 0
	s_nop 0
	s_nop 0
	s_nop 0
	s_nop 0
	s_nop 0
	s_nop 0
	s_nop 0
	s_nop 0
	s_nop 0
	s_nop 0
	s_nop 0
	s_nop 0
	s_nop 0
	s_nop 0
	s_nop 0
	s_nop 0
	s_nop 0
	s_nop 0
	s_nop 0
	s_nop 0
	s_nop 0
	s_nop 0
	s_nop 0
	s_nop 0
	s_nop 0
	s_nop 0
	s_nop 0
	s_nop 0
	s_nop 0
	s_nop 0
	s_nop 0
	s_nop 0
	s_nop 0
	s_nop 0
	s_nop 0
	s_nop 0
	s_nop 0
	s_nop 0
	s_nop 0
	s_nop 0
	s_nop 0
	s_nop 0
	s_nop 0
	s_nop 0
	s_nop 0
	s_nop 0
	s_nop 0
	s_nop 0
	s_nop 0
	s_nop 0
	s_nop 0
	s_nop 0
	s_nop 0
	s_nop 0
	s_nop 0
	s_nop 0
	s_nop 0
	s_nop 0
	s_nop 0
	s_nop 0
	s_nop 0
	s_nop 0
	s_nop 0
	s_nop 0
	s_nop 0
	s_nop 0
	s_nop 0
